# LayerNorm 2 row loops: gain/bias vectors loaded once before the loop instead of per row pair in load -> vmcnt(0) ladders behind the output stores
# speedup vs baseline: 1.0033x; 1.0033x over previous
; DI unsigned pk2(float lo, float hi) { const f32x2 v = {lo, hi}; const hwbf16x2 b = __builtin_convertvector(v, hwbf16x2); return __builtin_bit_cast(unsigned, b); }
; DI void ln_row(const float* xrow, const float* g, const float* b, float* orow, bf16_t* obf, int lane) {
;     const f32x4* xr = (const f32x4*)xrow + lane;
;     f32x4 v[4]; float s = 0.f;
; #pragma unroll
;     for (int j = 0; j < 4; ++j) { v[j] = xr[64 * j]; s += (v[j][0] + v[j][1]) + (v[j][2] + v[j][3]); }
;     const float mean = wave_sum(s, lane) * (1.f / 1024.f); float s2 = 0.f;
; #pragma unroll
;     for (int j = 0; j < 4; ++j) { v[j] = v[j] - mean; s2 += (v[j][0] * v[j][0] + v[j][1] * v[j][1]) + (v[j][2] * v[j][2] + v[j][3] * v[j][3]); }
;     const float rstd = 1.f / sqrtf(wave_sum(s2, lane) * (1.f / 1024.f) + EPS);
; #pragma unroll
;     for (int j = 0; j < 4; ++j) { const f32x4 gg = ((const f32x4*)g)[lane + 64 * j], bb = ((const f32x4*)b)[lane + 64 * j]; const f32x4 o = v[j] * rstd * gg + bb;
;         ((f32x4*)orow)[lane + 64 * j] = o;
;         if (obf) { u32x2 w; w.x = pk2(o[0], o[1]); w.y = pk2(o[2], o[3]); ((u32x2*)obf)[lane + 64 * j] = w; } }
; DI void ln_rows2_f32(float* xa, float* xb, const float* g, const float* b, int lane, bool two) {
;     ...
;     for (int j = 0; j < 4; ++j) { const f32x4 gg = ((const f32x4*)g)[lane + 64 * j], bb = ((const f32x4*)b)[lane + 64 * j];
; #pragma unroll
;         for (int r = 0; r < 2; ++r) if (r == 0 || two) xr[r][lane + 64 * j] = v[r][j] * rstd[r] * gg + bb; }
.LBB0_2100:
	s_or_b64 exec, exec, s[16:17]
	v_readlane_b32 s2, v254, 2
	v_readlane_b32 s3, v254, 3
	s_waitcnt lgkmcnt(0)
	s_barrier
	s_load_dwordx4 s[16:19], s[2:3], 0xd8
	s_load_dwordx4 s[20:23], s[2:3], 0xf0
	s_mov_b32 s2, s77
	v_mbcnt_lo_u32_b32 v39, -1, 0
	v_mbcnt_hi_u32_b32 v39, -1, v39
	v_readlane_b32 s14, v254, 0
	v_lshl_or_b32 v0, s2, 6, v39
	s_mov_b32 s3, s14
	v_readfirstlane_b32 s2, v0
	s_ashr_i32 s12, s2, 6
	s_mov_b32 s2, s87
	s_lshl_b32 s2, s2, 3
	s_add_i32 s24, s2, s12
	s_lshl_b32 s7, s3, 3
	v_readlane_b32 s2, v254, 63
	v_readlane_b32 s3, v255, 0
	s_lshl_b64 s[2:3], s[2:3], 2
	s_waitcnt lgkmcnt(0)
	s_add_u32 s26, s16, s2
	s_addc_u32 s27, s17, s3
	s_add_u32 s28, s18, s2
	s_addc_u32 s29, s19, s3
	v_readlane_b32 s15, v254, 1
	s_cmp_lt_i32 s24, 0x8000
	s_cselect_b64 s[14:15], -1, 0
	v_readlane_b32 s16, v254, 56
	v_readlane_b32 s17, v254, 57
	v_cndmask_b32_e64 v0, 0, 1, s[14:15]
	v_and_b32_e32 v38, 63, v39
	s_mov_b64 s[2:3], -1
	s_andn2_b64 vcc, exec, s[16:17]
	v_cmp_ne_u32_e64 s[16:17], 1, v0
	s_cbranch_vccnz .LBB0_2113
	s_and_b64 vcc, exec, s[16:17]
	s_cbranch_vccnz .LBB0_2112
	v_lshlrev_b32_e32 v0, 2, v38
	v_xor_b32_e32 v58, 4, v0
	v_xor_b32_e32 v59, 8, v0
	v_xor_b32_e32 v60, 16, v0
	v_xor_b32_e32 v61, 32, v0
	v_xor_b32_e32 v62, 64, v0
	v_xor_b32_e32 v63, 0x80, v0
	v_lshlrev_b32_e32 v0, 4, v38
	v_lshl_add_u64 v[40:41], s[26:27], 0, v[0:1]
	v_lshl_add_u64 v[42:43], s[28:29], 0, v[0:1]
	v_lshl_add_u64 v[44:45], s[20:21], 0, v[0:1]
	s_mov_b32 s2, s24
	global_load_dwordx4 v[108:111], v[40:41], off
	global_load_dwordx4 v[112:115], v[42:43], off
	global_load_dwordx4 v[116:119], v[40:41], off offset:1024
	global_load_dwordx4 v[120:123], v[42:43], off offset:1024
	global_load_dwordx4 v[124:127], v[40:41], off offset:2048
	global_load_dwordx4 v[128:131], v[42:43], off offset:2048
	global_load_dwordx4 v[132:135], v[40:41], off offset:3072
	global_load_dwordx4 v[136:139], v[42:43], off offset:3072
	s_waitcnt vmcnt(0)
	s_branch .LBB0_2104

; DI float bperm(float v, int srclane) { return __int_as_float(__builtin_amdgcn_ds_bpermute(srclane << 2, __float_as_int(v))); }
; DI void ln_rows2_f32(float* xa, float* xb, const float* g, const float* b, int lane, bool two) {
;     f32x4* xr[2] = {(f32x4*)xa, (f32x4*)xb}; f32x4 v[2][4]; float s[2] = {0.f, 0.f}, s2[2] = {0.f, 0.f}, mean[2], rstd[2];
; #pragma unroll
;     for (int r = 0; r < 2; ++r)
; #pragma unroll
;         for (int j = 0; j < 4; ++j) v[r][j] = xr[r][lane + 64 * j];
; #pragma unroll
;     for (int r = 0; r < 2; ++r)
; #pragma unroll
;         for (int j = 0; j < 4; ++j) s[r] += (v[r][j][0] + v[r][j][1]) + (v[r][j][2] + v[r][j][3]);
; #pragma unroll
;     for (int o = 1; o < 64; o <<= 1) { s[0] += bperm(s[0], lane ^ o); s[1] += bperm(s[1], lane ^ o); }
; #pragma unroll
;     for (int r = 0; r < 2; ++r) { mean[r] = s[r] * (1.f / 1024.f);
; #pragma unroll
;         for (int j = 0; j < 4; ++j) { v[r][j] = v[r][j] - mean[r]; s2[r] += (v[r][j][0] * v[r][j][0] + v[r][j][1] * v[r][j][1]) + (v[r][j][2] * v[r][j][2] + v[r][j][3] * v[r][j][3]); } }
; #pragma unroll
;     for (int o = 1; o < 64; o <<= 1) { s2[0] += bperm(s2[0], lane ^ o); s2[1] += bperm(s2[1], lane ^ o); }
.LBB0_2104:
	s_add_i32 s13, s2, s7
	s_cmp_lt_i32 s13, 0x8000
	s_cselect_b32 s20, s13, s2
	s_ashr_i32 s3, s2, 31
	s_lshl_b64 s[14:15], s[2:3], 12
	v_lshl_add_u64 v[46:47], v[44:45], 0, s[14:15]
	global_load_dwordx4 v[30:33], v[46:47], off
	global_load_dwordx4 v[26:29], v[46:47], off offset:1024
	global_load_dwordx4 v[14:17], v[46:47], off offset:2048
	global_load_dwordx4 v[10:13], v[46:47], off offset:3072
	s_ashr_i32 s21, s20, 31
	s_lshl_b64 s[14:15], s[20:21], 12
	v_lshl_add_u64 v[48:49], v[44:45], 0, s[14:15]
	global_load_dwordx4 v[22:25], v[48:49], off
	global_load_dwordx4 v[18:21], v[48:49], off offset:1024
	global_load_dwordx4 v[6:9], v[48:49], off offset:2048
	global_load_dwordx4 v[2:5], v[48:49], off offset:3072
	s_mov_b32 s3, 0xf800000
	s_cmp_lg_u32 s2, s20
	s_cselect_b64 s[34:35], -1, 0
	s_cmp_eq_u32 s2, s20
	s_waitcnt vmcnt(7)
	v_mov_b32_e32 v34, v31
	v_mov_b32_e32 v35, v32
	v_mov_b32_e32 v36, v30
	v_mov_b32_e32 v37, v33
	s_waitcnt vmcnt(6)
	v_mov_b32_e32 v50, v27
	v_mov_b32_e32 v51, v28
	v_mov_b32_e32 v52, v26
	v_mov_b32_e32 v53, v29
	s_waitcnt vmcnt(5)
	v_add_f32_e32 v54, v14, v15
	v_add_f32_e32 v56, v16, v17
	s_waitcnt vmcnt(4)
	v_mov_b32_e32 v55, v12
	v_mov_b32_e32 v57, v13
	v_pk_add_f32 v[34:35], v[34:35], v[36:37]
	v_pk_add_f32 v[36:37], v[50:51], v[52:53]
	v_pk_add_f32 v[50:51], v[54:55], v[56:57]
	s_waitcnt vmcnt(3)
	v_mov_b32_e32 v52, v23
	v_mov_b32_e32 v53, v24
	v_mov_b32_e32 v54, v22
	v_mov_b32_e32 v55, v25
	s_waitcnt vmcnt(2)
	v_mov_b32_e32 v56, v19
	v_mov_b32_e32 v57, v20
	v_mov_b32_e32 v66, v18
	v_mov_b32_e32 v67, v21
	v_add_f32_e32 v0, v34, v35
	v_pk_add_f32 v[34:35], v[36:37], v[36:37] op_sel:[0,1] op_sel_hi:[1,0]
	v_pk_add_f32 v[36:37], v[52:53], v[54:55]
	v_pk_add_f32 v[52:53], v[56:57], v[66:67]
	v_mov_b32_e32 v65, v10
	v_add_f32_e32 v64, 0, v0
	v_mov_b32_e32 v35, v11
	v_add_f32_e32 v0, v36, v37
	v_pk_add_f32 v[36:37], v[52:53], v[52:53] op_sel:[0,1] op_sel_hi:[1,0]
	s_waitcnt vmcnt(1)
	v_add_f32_e32 v68, v6, v7
	v_add_f32_e32 v70, v8, v9
	s_waitcnt vmcnt(0)
	v_mov_b32_e32 v73, v2
	v_mov_b32_e32 v69, v4
	v_mov_b32_e32 v71, v5
	v_pk_add_f32 v[34:35], v[64:65], v[34:35]
	v_add_f32_e32 v72, 0, v0
	v_mov_b32_e32 v37, v3
	v_pk_add_f32 v[54:55], v[68:69], v[70:71]
	v_pk_add_f32 v[34:35], v[34:35], v[50:51]
	v_pk_add_f32 v[36:37], v[72:73], v[36:37]
	v_add_f32_e32 v0, v34, v35
	v_pk_add_f32 v[34:35], v[36:37], v[54:55]
	s_nop 0
	v_add_f32_e32 v34, v34, v35
	ds_bpermute_b32 v35, v58, v0
	ds_bpermute_b32 v36, v58, v34
	s_waitcnt lgkmcnt(1)
	v_add_f32_e32 v0, v0, v35
	ds_bpermute_b32 v35, v59, v0
	s_waitcnt lgkmcnt(1)
	v_add_f32_e32 v34, v34, v36
	ds_bpermute_b32 v36, v59, v34
	s_waitcnt lgkmcnt(1)
	v_add_f32_e32 v0, v0, v35
	ds_bpermute_b32 v35, v60, v0
	s_waitcnt lgkmcnt(1)
	v_add_f32_e32 v34, v34, v36
	ds_bpermute_b32 v36, v60, v34
	s_waitcnt lgkmcnt(1)
	v_add_f32_e32 v0, v0, v35
	ds_bpermute_b32 v35, v61, v0
	s_waitcnt lgkmcnt(1)
	v_add_f32_e32 v34, v34, v36
	ds_bpermute_b32 v36, v61, v34
	s_waitcnt lgkmcnt(1)
	v_add_f32_e32 v0, v0, v35
	ds_bpermute_b32 v35, v62, v0
	s_waitcnt lgkmcnt(1)
	v_add_f32_e32 v34, v34, v36
	ds_bpermute_b32 v36, v62, v34
	s_waitcnt lgkmcnt(1)
	v_add_f32_e32 v0, v0, v35
	ds_bpermute_b32 v35, v63, v0
	s_waitcnt lgkmcnt(1)
	v_add_f32_e32 v34, v34, v36
	ds_bpermute_b32 v36, v63, v34
	s_waitcnt lgkmcnt(1)
	v_add_f32_e32 v0, v0, v35
	v_fmamk_f32 v55, v0, 0xba800000, v31
	v_fmamk_f32 v54, v0, 0xba800000, v30
	v_fmamk_f32 v33, v0, 0xba800000, v33
	v_fmac_f32_e32 v32, 0xba800000, v0
	v_fmamk_f32 v53, v0, 0xba800000, v29
	v_fmamk_f32 v52, v0, 0xba800000, v28
	v_fmamk_f32 v27, v0, 0xba800000, v27
	v_fmac_f32_e32 v26, 0xba800000, v0
	s_waitcnt lgkmcnt(0)
	v_add_f32_e32 v66, v34, v36
	v_pk_mul_f32 v[28:29], v[32:33], v[32:33]
	v_pk_mul_f32 v[30:31], v[54:55], v[54:55]
	v_pk_mul_f32 v[34:35], v[52:53], v[52:53]
	v_pk_mul_f32 v[36:37], v[26:27], v[26:27]
	v_fmamk_f32 v50, v0, 0xba800000, v16
	v_fmac_f32_e32 v14, 0xba800000, v0
	v_pk_mov_b32 v[56:57], v[30:31], v[28:29] op_sel:[1,0]
	v_mov_b32_e32 v31, v29
	v_pk_mov_b32 v[28:29], v[36:37], v[34:35] op_sel:[1,0]
	v_mov_b32_e32 v37, v35
	v_fmamk_f32 v51, v0, 0xba800000, v17
	v_fmamk_f32 v15, v0, 0xba800000, v15
	v_fmamk_f32 v13, v0, 0xba800000, v13
	v_fmamk_f32 v12, v0, 0xba800000, v12
	v_fmamk_f32 v11, v0, 0xba800000, v11
	v_fmac_f32_e32 v10, 0xba800000, v0
	v_mul_f32_e32 v0, v14, v14
	v_mul_f32_e32 v16, v50, v50
	v_fmamk_f32 v17, v66, 0xba800000, v21
	v_pk_add_f32 v[30:31], v[56:57], v[30:31]
	v_pk_add_f32 v[28:29], v[28:29], v[36:37]
	v_pk_fma_f32 v[34:35], v[14:15], v[14:15], v[0:1] op_sel_hi:[1,1,0]
	v_pk_fma_f32 v[64:65], v[50:51], v[50:51], v[16:17] op_sel_hi:[1,1,0]
	v_pk_add_f32 v[30:31], v[30:31], v[30:31] op_sel_hi:[0,1]
	v_pk_add_f32 v[28:29], v[28:29], v[28:29] op_sel_hi:[0,1]
	v_fmamk_f32 v25, v66, 0xba800000, v25
	v_fmamk_f32 v23, v66, 0xba800000, v23
	v_mul_f32_e32 v34, v10, v10
	v_mul_f32_e32 v64, v11, v11
	v_mul_f32_e32 v30, v12, v12
	v_mul_f32_e32 v28, v13, v13
	v_fmamk_f32 v24, v66, 0xba800000, v24
	v_fmac_f32_e32 v22, 0xba800000, v66
	v_mul_f32_e32 v0, v23, v23
	v_mul_f32_e32 v16, v25, v25
	v_pk_add_f32 v[34:35], v[34:35], v[64:65]
	v_pk_add_f32 v[28:29], v[30:31], v[28:29]
	v_fmac_f32_e32 v0, v22, v22
	v_fmac_f32_e32 v16, v24, v24
	v_pk_add_f32 v[28:29], v[34:35], v[28:29]
	v_fmamk_f32 v19, v66, 0xba800000, v19
	v_add_f32_e32 v0, v0, v16
	v_add_f32_e32 v21, v28, v29
	v_fmamk_f32 v16, v66, 0xba800000, v20
	v_fmac_f32_e32 v18, 0xba800000, v66
	v_mul_f32_e32 v20, v19, v19
	v_mul_f32_e32 v28, v17, v17
	v_fmac_f32_e32 v20, v18, v18
	v_fmac_f32_e32 v28, v16, v16
	v_add_f32_e32 v20, v20, v28
	v_fmamk_f32 v9, v66, 0xba800000, v9
	v_fmamk_f32 v7, v66, 0xba800000, v7
	v_add_f32_e32 v0, v0, v20
	v_fmamk_f32 v8, v66, 0xba800000, v8
	v_fmac_f32_e32 v6, 0xba800000, v66
	v_mul_f32_e32 v20, v7, v7
	v_mul_f32_e32 v28, v9, v9
	v_fmac_f32_e32 v20, v6, v6
	v_fmac_f32_e32 v28, v8, v8
	v_add_f32_e32 v20, v20, v28
	ds_bpermute_b32 v28, v58, v21
	v_fmamk_f32 v5, v66, 0xba800000, v5
	v_fmamk_f32 v3, v66, 0xba800000, v3
	v_add_f32_e32 v0, v20, v0
	v_fmamk_f32 v4, v66, 0xba800000, v4
	s_waitcnt lgkmcnt(0)
; DI void ln_rows2_f32(float* xa, float* xb, const float* g, const float* b, int lane, bool two) {
;     ...
; #pragma unroll
;     for (int r = 0; r < 2; ++r) rstd[r] = 1.f / sqrtf(s2[r] * (1.f / 1024.f) + EPS);
; #pragma unroll
;     for (int j = 0; j < 4; ++j) { const f32x4 gg = ((const f32x4*)g)[lane + 64 * j], bb = ((const f32x4*)b)[lane + 64 * j];
; #pragma unroll
;         for (int r = 0; r < 2; ++r) if (r == 0 || two) xr[r][lane + 64 * j] = v[r][j] * rstd[r] * gg + bb; }
	v_add_f32_e32 v21, v21, v28
	ds_bpermute_b32 v28, v59, v21
	v_fmac_f32_e32 v2, 0xba800000, v66
	v_mul_f32_e32 v20, v3, v3
	v_mul_f32_e32 v29, v5, v5
	v_fmac_f32_e32 v20, v2, v2
	s_waitcnt lgkmcnt(0)
	v_add_f32_e32 v21, v21, v28
	ds_bpermute_b32 v28, v60, v21
	v_fmac_f32_e32 v29, v4, v4
	v_add_f32_e32 v20, v20, v29
	v_add_f32_e32 v0, v20, v0
	ds_bpermute_b32 v20, v58, v0
	s_waitcnt lgkmcnt(1)
	v_add_f32_e32 v21, v21, v28
	ds_bpermute_b32 v28, v61, v21
	s_waitcnt lgkmcnt(1)
	v_add_f32_e32 v0, v0, v20
	ds_bpermute_b32 v20, v59, v0
	s_waitcnt lgkmcnt(1)
	v_add_f32_e32 v21, v21, v28
	s_nop 1
	v_mov_b32_e32 v28, v108
	v_mov_b32_e32 v29, v109
	v_mov_b32_e32 v30, v110
	v_mov_b32_e32 v31, v111
	s_nop 1
	v_mov_b32_e32 v34, v112
	v_mov_b32_e32 v35, v113
	v_mov_b32_e32 v36, v114
	v_mov_b32_e32 v37, v115
	ds_bpermute_b32 v56, v62, v21
	s_waitcnt lgkmcnt(1)
	v_add_f32_e32 v0, v0, v20
	ds_bpermute_b32 v20, v60, v0
	s_waitcnt lgkmcnt(1)
	v_add_f32_e32 v21, v21, v56
	ds_bpermute_b32 v56, v63, v21
	s_waitcnt lgkmcnt(1)
	v_add_f32_e32 v0, v0, v20
	ds_bpermute_b32 v20, v61, v0
	s_waitcnt lgkmcnt(1)
	v_add_f32_e32 v21, v21, v56
	v_fmamk_f32 v21, v21, 0x3a800000, v202
	v_mul_f32_e32 v56, 0x4f800000, v21
	v_cmp_gt_f32_e32 vcc, s3, v21
	s_waitcnt lgkmcnt(0)
	v_add_f32_e32 v0, v0, v20
	ds_bpermute_b32 v20, v62, v0
	v_cndmask_b32_e32 v21, v21, v56, vcc
	v_sqrt_f32_e32 v56, v21
	s_waitcnt lgkmcnt(0)
	v_add_f32_e32 v0, v0, v20
	v_add_u32_e32 v57, -1, v56
	v_fma_f32 v64, -v57, v56, v21
	v_cmp_ge_f32_e64 s[18:19], 0, v64
	v_add_u32_e32 v64, 1, v56
	ds_bpermute_b32 v20, v63, v0
	v_cndmask_b32_e64 v57, v56, v57, s[18:19]
	v_fma_f32 v56, -v64, v56, v21
	v_cmp_lt_f32_e64 s[18:19], 0, v56
	s_waitcnt lgkmcnt(0)
	v_add_f32_e32 v0, v0, v20
	v_cndmask_b32_e64 v56, v57, v64, s[18:19]
	v_mul_f32_e32 v57, 0x37800000, v56
	v_cndmask_b32_e32 v56, v56, v57, vcc
	v_cmp_class_f32_e32 vcc, v21, v205
	v_fmamk_f32 v0, v0, 0x3a800000, v202
	v_mul_f32_e32 v65, 0x4f800000, v0
	v_cndmask_b32_e32 v21, v56, v21, vcc
	v_div_scale_f32 v56, s[14:15], v21, v21, 1.0
	v_rcp_f32_e32 v57, v56
	v_cmp_gt_f32_e64 s[18:19], s3, v0
	v_fma_f32 v20, -v56, v57, 1.0
	s_nop 0
	v_cndmask_b32_e64 v0, v0, v65, s[18:19]
	v_fmac_f32_e32 v57, v20, v57
	v_div_scale_f32 v20, vcc, 1.0, v21, 1.0
	v_sqrt_f32_e32 v65, v0
	v_mul_f32_e32 v64, v20, v57
	v_fma_f32 v66, -v56, v64, v20
	v_fmac_f32_e32 v64, v66, v57
	v_fma_f32 v20, -v56, v64, v20
	v_add_u32_e32 v56, -1, v65
	v_fma_f32 v66, -v56, v65, v0
	v_cmp_ge_f32_e64 s[20:21], 0, v66
	v_add_u32_e32 v66, 1, v65
	v_div_fmas_f32 v20, v20, v57, v64
	v_cndmask_b32_e64 v56, v65, v56, s[20:21]
	v_fma_f32 v65, -v66, v65, v0
	v_cmp_lt_f32_e64 s[20:21], 0, v65
	s_nop 1
	v_cndmask_b32_e64 v56, v56, v66, s[20:21]
	v_mul_f32_e32 v65, 0x37800000, v56
	v_cndmask_b32_e64 v56, v56, v65, s[18:19]
	v_cmp_class_f32_e64 s[18:19], v0, v205
	s_nop 1
	v_cndmask_b32_e64 v0, v56, v0, s[18:19]
	v_div_scale_f32 v65, s[2:3], v0, v0, 1.0
	v_rcp_f32_e32 v66, v65
	v_div_fixup_f32 v56, v20, v21, 1.0
	s_mov_b64 s[2:3], -1
	v_fma_f32 v20, -v65, v66, 1.0
	v_fmac_f32_e32 v66, v20, v66
	v_div_scale_f32 v20, vcc, 1.0, v0, 1.0
	v_mul_f32_e32 v21, v20, v66
	v_fma_f32 v57, -v65, v21, v20
	v_fmac_f32_e32 v21, v57, v66
	v_fma_f32 v20, -v65, v21, v20
	v_div_fmas_f32 v20, v20, v66, v21
	v_mov_b32_e32 v57, v56
	v_div_fixup_f32 v0, v20, v0, 1.0
	v_pk_mul_f32 v[20:21], v[54:55], v[56:57] op_sel_hi:[1,0]
	v_pk_mul_f32 v[32:33], v[32:33], v[56:57] op_sel_hi:[1,0]
	s_nop 0
	v_pk_fma_f32 v[64:65], v[28:29], v[20:21], v[34:35]
	v_pk_fma_f32 v[66:67], v[30:31], v[32:33], v[36:37]
	v_pk_mul_f32 v[20:21], v[26:27], v[56:57]
	global_store_dwordx4 v[46:47], v[64:67], off
	s_cbranch_scc1 .LBB0_2106
	v_pk_mul_f32 v[24:25], v[24:25], v[0:1] op_sel_hi:[1,0]
	v_pk_mul_f32 v[22:23], v[22:23], v[0:1] op_sel_hi:[1,0]
	v_pk_fma_f32 v[24:25], v[30:31], v[24:25], v[36:37]
	v_pk_fma_f32 v[22:23], v[28:29], v[22:23], v[34:35]
	global_store_dwordx4 v[48:49], v[22:25], off
	s_nop 1
	v_mov_b32_e32 v22, v116
	v_mov_b32_e32 v23, v117
	v_mov_b32_e32 v24, v118
	v_mov_b32_e32 v25, v119
	s_nop 0
	s_nop 1
	v_mov_b32_e32 v26, v120
	v_mov_b32_e32 v27, v121
	v_mov_b32_e32 v28, v122
	v_mov_b32_e32 v29, v123
	v_mov_b32_e32 v30, v56
	v_mov_b32_e32 v31, v56
	v_pk_mul_f32 v[32:33], v[16:17], v[0:1] op_sel_hi:[1,0]
	v_pk_mul_f32 v[16:17], v[52:53], v[30:31]
	v_pk_mul_f32 v[34:35], v[18:19], v[0:1] op_sel_hi:[1,0]
	s_mov_b64 s[2:3], 0
	s_nop 0
	v_pk_fma_f32 v[18:19], v[16:17], v[24:25], v[28:29]
	v_pk_fma_f32 v[16:17], v[20:21], v[22:23], v[26:27]
	v_pk_fma_f32 v[24:25], v[32:33], v[24:25], v[28:29]
	v_pk_fma_f32 v[22:23], v[34:35], v[22:23], v[26:27]
	global_store_dwordx4 v[46:47], v[16:19], off offset:1024
	global_store_dwordx4 v[48:49], v[22:25], off offset:1024
.LBB0_2106:
	s_andn2_b64 vcc, exec, s[2:3]
	s_cbranch_vccnz .LBB0_2108
	s_nop 1
	v_mov_b32_e32 v16, v116
	v_mov_b32_e32 v17, v117
	v_mov_b32_e32 v18, v118
	v_mov_b32_e32 v19, v119
	s_nop 1
	v_mov_b32_e32 v22, v120
	v_mov_b32_e32 v23, v121
	v_mov_b32_e32 v24, v122
	v_mov_b32_e32 v25, v123
	v_mov_b32_e32 v26, v56
	v_mov_b32_e32 v27, v56
	v_pk_mul_f32 v[26:27], v[52:53], v[26:27]
	s_nop 0
	v_pk_fma_f32 v[16:17], v[20:21], v[16:17], v[22:23]
	v_pk_fma_f32 v[18:19], v[26:27], v[18:19], v[24:25]
	global_store_dwordx4 v[46:47], v[16:19], off offset:1024
.LBB0_2108:
	s_nop 1
	v_mov_b32_e32 v16, v124
	v_mov_b32_e32 v17, v125
	v_mov_b32_e32 v18, v126
	v_mov_b32_e32 v19, v127
	s_nop 0
	s_nop 1
	v_mov_b32_e32 v20, v128
	v_mov_b32_e32 v21, v129
	v_mov_b32_e32 v22, v130
	v_mov_b32_e32 v23, v131
	v_mov_b32_e32 v24, v56
	v_mov_b32_e32 v25, v56
	v_pk_mul_f32 v[26:27], v[50:51], v[24:25]
	v_pk_mul_f32 v[14:15], v[14:15], v[56:57]
	s_mov_b64 s[2:3], -1
	s_andn2_b64 vcc, exec, s[34:35]
	v_pk_mul_f32 v[10:11], v[10:11], v[56:57]
	s_nop 0
	v_pk_fma_f32 v[28:29], v[26:27], v[18:19], v[22:23]
	v_pk_fma_f32 v[26:27], v[14:15], v[16:17], v[20:21]
	global_store_dwordx4 v[46:47], v[26:29], off offset:2048
	s_cbranch_vccnz .LBB0_2110
	v_pk_mul_f32 v[8:9], v[8:9], v[0:1] op_sel_hi:[1,0]
	v_pk_mul_f32 v[6:7], v[6:7], v[0:1] op_sel_hi:[1,0]
	v_pk_fma_f32 v[8:9], v[8:9], v[18:19], v[22:23]
	v_pk_fma_f32 v[6:7], v[6:7], v[16:17], v[20:21]
	global_store_dwordx4 v[48:49], v[6:9], off offset:2048
	s_nop 1
	v_mov_b32_e32 v6, v132
	v_mov_b32_e32 v7, v133
	v_mov_b32_e32 v8, v134
	v_mov_b32_e32 v9, v135
	s_nop 0
	s_nop 1
	v_mov_b32_e32 v14, v136
	v_mov_b32_e32 v15, v137
	v_mov_b32_e32 v16, v138
	v_mov_b32_e32 v17, v139
	v_pk_mul_f32 v[18:19], v[12:13], v[24:25]
	v_pk_mul_f32 v[20:21], v[4:5], v[0:1] op_sel_hi:[1,0]
	v_pk_mul_f32 v[22:23], v[2:3], v[0:1] op_sel_hi:[1,0]
	s_nop 0
	v_pk_fma_f32 v[4:5], v[18:19], v[8:9], v[16:17]
	v_pk_fma_f32 v[2:3], v[10:11], v[6:7], v[14:15]
	v_pk_fma_f32 v[8:9], v[20:21], v[8:9], v[16:17]
	v_pk_fma_f32 v[6:7], v[22:23], v[6:7], v[14:15]
	global_store_dwordx4 v[46:47], v[2:5], off offset:3072
	global_store_dwordx4 v[48:49], v[6:9], off offset:3072
	s_cbranch_execnz .LBB0_2103
	s_branch .LBB0_2111

; DI void ln_rows2_f32(float* xa, float* xb, const float* g, const float* b, int lane, bool two) {
;     ...
;     for (int j = 0; j < 4; ++j) { const f32x4 gg = ((const f32x4*)g)[lane + 64 * j], bb = ((const f32x4*)b)[lane + 64 * j];
; #pragma unroll
;         for (int r = 0; r < 2; ++r) if (r == 0 || two) xr[r][lane + 64 * j] = v[r][j] * rstd[r] * gg + bb; }
.LBB0_2111:
	s_nop 1
	v_mov_b32_e32 v2, v132
	v_mov_b32_e32 v3, v133
	v_mov_b32_e32 v4, v134
	v_mov_b32_e32 v5, v135
	s_nop 1
	v_mov_b32_e32 v6, v136
	v_mov_b32_e32 v7, v137
	v_mov_b32_e32 v8, v138
	v_mov_b32_e32 v9, v139
	v_mov_b32_e32 v57, v56
	v_pk_mul_f32 v[12:13], v[12:13], v[56:57]
	s_nop 0
	v_pk_fma_f32 v[2:3], v[10:11], v[2:3], v[6:7]
	v_pk_fma_f32 v[4:5], v[12:13], v[4:5], v[8:9]
	global_store_dwordx4 v[46:47], v[2:5], off offset:3072
	s_branch .LBB0_2103

; DI u32x4 pack8(const float (&v)[8]) { u32x4 w; w.x = pk2(v[0], v[1]); w.y = pk2(v[2], v[3]); w.z = pk2(v[4], v[5]); w.w = pk2(v[6], v[7]); return w; }
; DI void ln_rows2_bf16(bf16_t* xa, bf16_t* xb, const float* g, const float* b, int lane, bool two) {
;     ...
; #pragma unroll
;     for (int j = 0; j < 2; ++j) { const int c0 = (lane + 64 * j) * 8; const f32x4 g0 = *(const f32x4*)(g + c0), g1 = *(const f32x4*)(g + c0 + 4), b0 = *(const f32x4*)(b + c0), b1 = *(const f32x4*)(b + c0 + 4);
; #pragma unroll
;         for (int r = 0; r < 2; ++r) { float o[8];
; #pragma unroll
;             for (int k = 0; k < 4; ++k) { o[k] = v[r][j][k] * rstd[r] * g0[k] + b0[k]; o[4 + k] = v[r][j][4 + k] * rstd[r] * g1[k] + b1[k]; }
;             if (r == 0 || two) xr[r][lane + 64 * j] = pack8(o); } }
.LBB0_2113:
	s_andn2_b64 vcc, exec, s[2:3]
	s_cbranch_vccnz .LBB0_2631
	v_lshlrev_b32_e32 v2, 2, v38
	s_and_b64 vcc, exec, s[16:17]
	v_xor_b32_e32 v60, 0x80, v2
	s_cbranch_vccnz .LBB0_2121
	v_lshlrev_b32_e32 v0, 5, v38
	v_lshl_add_u64 v[18:19], s[26:27], 0, v[0:1]
	v_lshl_add_u64 v[20:21], s[28:29], 0, v[0:1]
	v_or_b32_e32 v0, 0x800, v0
	v_lshl_add_u64 v[22:23], s[26:27], 0, v[0:1]
	v_lshl_add_u64 v[24:25], s[28:29], 0, v[0:1]
	v_lshlrev_b32_e32 v0, 4, v38
	v_xor_b32_e32 v61, 4, v2
	v_xor_b32_e32 v62, 8, v2
	v_xor_b32_e32 v63, 16, v2
	v_xor_b32_e32 v64, 32, v2
	v_xor_b32_e32 v65, 64, v2
	v_lshl_add_u64 v[2:3], s[22:23], 0, v[0:1]
	s_mov_b64 s[2:3], 0x2800000
	v_lshl_add_u64 v[26:27], v[2:3], 0, s[2:3]
	global_load_dwordx4 v[140:143], v[18:19], off
	global_load_dwordx4 v[144:147], v[20:21], off
	global_load_dwordx4 v[148:151], v[18:19], off offset:16
	global_load_dwordx4 v[152:155], v[20:21], off offset:16
	global_load_dwordx4 v[156:159], v[22:23], off offset:16
	global_load_dwordx4 v[160:163], v[22:23], off
	global_load_dwordx4 v[164:167], v[24:25], off offset:16
	global_load_dwordx4 v[168:171], v[24:25], off
	s_waitcnt vmcnt(0)
	s_branch .LBB0_2117

; DI float bperm(float v, int srclane) { return __int_as_float(__builtin_amdgcn_ds_bpermute(srclane << 2, __float_as_int(v))); }
; DI void ln_rows2_bf16(bf16_t* xa, bf16_t* xb, const float* g, const float* b, int lane, bool two) {
;     u32x4* xr[2] = {(u32x4*)xa, (u32x4*)xb}; float v[2][2][8]; float s[2] = {0.f, 0.f}, s2[2] = {0.f, 0.f}, mean[2], rstd[2];
;     u32x4 raw[2][2];
; #pragma unroll
;     for (int r = 0; r < 2; ++r)
; #pragma unroll
;         for (int j = 0; j < 2; ++j) raw[r][j] = xr[r][lane + 64 * j];
; #pragma unroll
;     for (int r = 0; r < 2; ++r)
; #pragma unroll
;         for (int j = 0; j < 2; ++j) { unpack8(raw[r][j], v[r][j]);
; #pragma unroll
;             for (int k = 0; k < 8; ++k) s[r] += v[r][j][k]; }
; #pragma unroll
;     for (int o = 1; o < 64; o <<= 1) { s[0] += bperm(s[0], lane ^ o); s[1] += bperm(s[1], lane ^ o); }
; #pragma unroll
;     for (int r = 0; r < 2; ++r) { mean[r] = s[r] * (1.f / 1024.f);
; #pragma unroll
;         for (int j = 0; j < 2; ++j)
; #pragma unroll
;             for (int k = 0; k < 8; ++k) { v[r][j][k] -= mean[r]; s2[r] += v[r][j][k] * v[r][j][k]; } }
; #pragma unroll
;     for (int o = 1; o < 64; o <<= 1) { s2[0] += bperm(s2[0], lane ^ o); s2[1] += bperm(s2[1], lane ^ o); }
.LBB0_2117:
	s_add_i32 s13, s24, s7
	s_cmp_lt_i32 s13, 0x8000
	s_cselect_b32 s2, s13, s24
	s_ashr_i32 s25, s24, 31
	s_lshl_b64 s[14:15], s[24:25], 11
	s_ashr_i32 s3, s2, 31
	v_lshl_add_u64 v[30:31], v[26:27], 0, s[14:15]
	s_lshl_b64 s[14:15], s[2:3], 11
	v_lshl_add_u64 v[28:29], v[26:27], 0, s[14:15]
	global_load_dwordx4 v[6:9], v[30:31], off offset:1024
	global_load_dwordx4 v[10:13], v[30:31], off
	global_load_dwordx4 v[14:17], v[28:29], off offset:1024
	global_load_dwordx4 v[32:35], v[28:29], off
	s_mov_b32 s3, 0xf800000
	s_cmp_lg_u32 s24, s2
	s_cselect_b64 s[20:21], -1, 0
	s_cmp_eq_u32 s24, s2
	s_waitcnt vmcnt(3)
	v_lshlrev_b32_e32 v2, 16, v9
	s_waitcnt vmcnt(2)
	v_lshlrev_b32_e32 v42, 16, v10
	s_waitcnt vmcnt(0)
	v_lshlrev_b32_e32 v52, 16, v32
	v_and_b32_e32 v43, 0xffff0000, v10
	v_and_b32_e32 v53, 0xffff0000, v32
	v_add_f32_e32 v0, 0, v42
	v_add_f32_e32 v32, 0, v52
	v_lshlrev_b32_e32 v40, 16, v12
	v_and_b32_e32 v41, 0xffff0000, v12
	v_lshlrev_b32_e32 v12, 16, v11
	v_lshlrev_b32_e32 v50, 16, v34
	v_and_b32_e32 v51, 0xffff0000, v34
	v_lshlrev_b32_e32 v34, 16, v33
	v_add_f32_e32 v0, v0, v43
	v_add_f32_e32 v32, v32, v53
	v_and_b32_e32 v3, 0xffff0000, v9
	v_lshlrev_b32_e32 v4, 16, v8
	v_and_b32_e32 v5, 0xffff0000, v8
	v_lshlrev_b32_e32 v8, 16, v7
	v_and_b32_e32 v9, 0xffff0000, v7
	v_lshlrev_b32_e32 v36, 16, v6
	v_and_b32_e32 v37, 0xffff0000, v6
	v_lshlrev_b32_e32 v6, 16, v13
	v_and_b32_e32 v7, 0xffff0000, v13
	v_and_b32_e32 v13, 0xffff0000, v11
	v_lshlrev_b32_e32 v10, 16, v17
	v_and_b32_e32 v11, 0xffff0000, v17
	v_lshlrev_b32_e32 v58, 16, v16
	v_and_b32_e32 v59, 0xffff0000, v16
	v_lshlrev_b32_e32 v16, 16, v15
	v_and_b32_e32 v17, 0xffff0000, v15
	v_lshlrev_b32_e32 v66, 16, v14
	v_and_b32_e32 v67, 0xffff0000, v14
	v_lshlrev_b32_e32 v14, 16, v35
	v_and_b32_e32 v15, 0xffff0000, v35
	v_and_b32_e32 v35, 0xffff0000, v33
	v_add_f32_e32 v0, v0, v12
	v_add_f32_e32 v32, v32, v34
	v_add_f32_e32 v0, v0, v13
	v_add_f32_e32 v32, v32, v35
	v_add_f32_e32 v0, v0, v40
	v_add_f32_e32 v32, v32, v50
	v_add_f32_e32 v0, v0, v41
	v_add_f32_e32 v32, v32, v51
	v_add_f32_e32 v0, v0, v6
	v_add_f32_e32 v32, v32, v14
	v_add_f32_e32 v0, v0, v7
	v_add_f32_e32 v32, v32, v15
	v_add_f32_e32 v0, v0, v36
	v_add_f32_e32 v32, v32, v66
	v_add_f32_e32 v0, v0, v37
	v_add_f32_e32 v32, v32, v67
	v_add_f32_e32 v0, v0, v8
	v_add_f32_e32 v32, v32, v16
	v_add_f32_e32 v0, v0, v9
	v_add_f32_e32 v32, v32, v17
	v_add_f32_e32 v0, v0, v4
	v_add_f32_e32 v32, v32, v58
	v_add_f32_e32 v0, v0, v5
	v_add_f32_e32 v32, v32, v59
	v_add_f32_e32 v0, v0, v2
	v_add_f32_e32 v32, v32, v10
	v_add_f32_e32 v0, v0, v3
	v_add_f32_e32 v32, v32, v11
	ds_bpermute_b32 v33, v61, v0
	ds_bpermute_b32 v44, v61, v32
	s_waitcnt lgkmcnt(1)
	v_add_f32_e32 v0, v0, v33
	s_waitcnt lgkmcnt(0)
	v_add_f32_e32 v32, v32, v44
	ds_bpermute_b32 v33, v62, v0
	ds_bpermute_b32 v44, v62, v32
	s_waitcnt lgkmcnt(1)
	v_add_f32_e32 v0, v0, v33
	s_waitcnt lgkmcnt(0)
	v_add_f32_e32 v32, v32, v44
	ds_bpermute_b32 v33, v63, v0
	ds_bpermute_b32 v44, v63, v32
	s_waitcnt lgkmcnt(1)
	v_add_f32_e32 v0, v0, v33
	s_waitcnt lgkmcnt(0)
	v_add_f32_e32 v32, v32, v44
	ds_bpermute_b32 v33, v64, v0
	ds_bpermute_b32 v44, v64, v32
	s_waitcnt lgkmcnt(1)
	v_add_f32_e32 v0, v0, v33
	s_waitcnt lgkmcnt(0)
	v_add_f32_e32 v32, v32, v44
	ds_bpermute_b32 v33, v65, v0
	ds_bpermute_b32 v44, v65, v32
	s_waitcnt lgkmcnt(1)
	v_add_f32_e32 v0, v0, v33
	s_waitcnt lgkmcnt(0)
	v_add_f32_e32 v32, v32, v44
	ds_bpermute_b32 v33, v60, v0
	ds_bpermute_b32 v44, v60, v32
	s_waitcnt lgkmcnt(1)
	v_add_f32_e32 v0, v0, v33
	s_waitcnt lgkmcnt(0)
	v_add_f32_e32 v32, v32, v44
	v_mul_f32_e32 v0, 0x3a800000, v0
	v_mul_f32_e32 v32, 0x3a800000, v32
	v_pk_add_f32 v[68:69], v[42:43], v[0:1] op_sel_hi:[1,0] neg_lo:[0,1] neg_hi:[0,1]
	v_pk_add_f32 v[56:57], v[52:53], v[32:33] op_sel_hi:[1,0] neg_lo:[0,1] neg_hi:[0,1]
	v_pk_add_f32 v[48:49], v[2:3], v[0:1] op_sel_hi:[1,0] neg_lo:[0,1] neg_hi:[0,1]
	v_pk_add_f32 v[54:55], v[34:35], v[32:33] op_sel_hi:[1,0] neg_lo:[0,1] neg_hi:[0,1]
	v_pk_add_f32 v[34:35], v[58:59], v[32:33] op_sel_hi:[1,0] neg_lo:[0,1] neg_hi:[0,1]
	v_pk_mul_f32 v[2:3], v[68:69], v[68:69]
	v_pk_mul_f32 v[58:59], v[56:57], v[56:57]
	v_pk_add_f32 v[70:71], v[12:13], v[0:1] op_sel_hi:[1,0] neg_lo:[0,1] neg_hi:[0,1]
	v_pk_add_f32 v[72:73], v[40:41], v[0:1] op_sel_hi:[1,0] neg_lo:[0,1] neg_hi:[0,1]
	v_pk_add_f32 v[74:75], v[6:7], v[0:1] op_sel_hi:[1,0] neg_lo:[0,1] neg_hi:[0,1]
	v_pk_add_f32 v[42:43], v[36:37], v[0:1] op_sel_hi:[1,0] neg_lo:[0,1] neg_hi:[0,1]
	v_pk_add_f32 v[44:45], v[8:9], v[0:1] op_sel_hi:[1,0] neg_lo:[0,1] neg_hi:[0,1]
	v_pk_add_f32 v[46:47], v[4:5], v[0:1] op_sel_hi:[1,0] neg_lo:[0,1] neg_hi:[0,1]
	v_pk_add_f32 v[40:41], v[66:67], v[32:33] op_sel_hi:[1,0] neg_lo:[0,1] neg_hi:[0,1]
	v_pk_mul_f32 v[66:67], v[54:55], v[54:55]
	v_add_f32_e32 v0, v2, v3
	v_add_f32_e32 v2, v58, v59
	v_pk_add_f32 v[52:53], v[50:51], v[32:33] op_sel_hi:[1,0] neg_lo:[0,1] neg_hi:[0,1]
	v_add_f32_e32 v2, v66, v2
	v_pk_mul_f32 v[76:77], v[52:53], v[52:53]
	v_add_f32_e32 v2, v67, v2
	v_pk_add_f32 v[50:51], v[14:15], v[32:33] op_sel_hi:[1,0] neg_lo:[0,1] neg_hi:[0,1]
	v_add_f32_e32 v2, v76, v2
	v_pk_mul_f32 v[78:79], v[50:51], v[50:51]
	v_add_f32_e32 v2, v77, v2
	v_add_f32_e32 v2, v78, v2
	v_pk_mul_f32 v[80:81], v[40:41], v[40:41]
	v_add_f32_e32 v2, v79, v2
	v_pk_add_f32 v[36:37], v[16:17], v[32:33] op_sel_hi:[1,0] neg_lo:[0,1] neg_hi:[0,1]
	v_add_f32_e32 v2, v80, v2
	v_pk_mul_f32 v[82:83], v[36:37], v[36:37]
	v_add_f32_e32 v2, v81, v2
	v_add_f32_e32 v2, v82, v2
	v_pk_mul_f32 v[84:85], v[34:35], v[34:35]
	v_add_f32_e32 v2, v83, v2
	v_pk_add_f32 v[32:33], v[10:11], v[32:33] op_sel_hi:[1,0] neg_lo:[0,1] neg_hi:[0,1]
	v_add_f32_e32 v2, v84, v2
	v_pk_mul_f32 v[86:87], v[32:33], v[32:33]
	v_add_f32_e32 v2, v85, v2
	v_add_f32_e32 v2, v86, v2
	v_add_f32_e32 v2, v87, v2
	ds_bpermute_b32 v3, v61, v2
	v_pk_mul_f32 v[4:5], v[70:71], v[70:71]
	v_pk_mul_f32 v[6:7], v[72:73], v[72:73]
	v_add_f32_e32 v0, v4, v0
	v_add_f32_e32 v0, v5, v0
	s_waitcnt lgkmcnt(0)
; DI float bperm(float v, int srclane) { return __int_as_float(__builtin_amdgcn_ds_bpermute(srclane << 2, __float_as_int(v))); }
; DI u32x4 pack8(const float (&v)[8]) { u32x4 w; w.x = pk2(v[0], v[1]); w.y = pk2(v[2], v[3]); w.z = pk2(v[4], v[5]); w.w = pk2(v[6], v[7]); return w; }
; DI void ln_rows2_bf16(bf16_t* xa, bf16_t* xb, const float* g, const float* b, int lane, bool two) {
;     ...
;     for (int o = 1; o < 64; o <<= 1) { s2[0] += bperm(s2[0], lane ^ o); s2[1] += bperm(s2[1], lane ^ o); }
; #pragma unroll
;     for (int r = 0; r < 2; ++r) rstd[r] = 1.f / sqrtf(s2[r] * (1.f / 1024.f) + EPS);
; #pragma unroll
;     for (int j = 0; j < 2; ++j) { const int c0 = (lane + 64 * j) * 8; const f32x4 g0 = *(const f32x4*)(g + c0), g1 = *(const f32x4*)(g + c0 + 4), b0 = *(const f32x4*)(b + c0), b1 = *(const f32x4*)(b + c0 + 4);
; #pragma unroll
;         for (int r = 0; r < 2; ++r) { float o[8];
; #pragma unroll
;             for (int k = 0; k < 4; ++k) { o[k] = v[r][j][k] * rstd[r] * g0[k] + b0[k]; o[4 + k] = v[r][j][4 + k] * rstd[r] * g1[k] + b1[k]; }
;             if (r == 0 || two) xr[r][lane + 64 * j] = pack8(o); } }
	v_add_f32_e32 v2, v2, v3
	v_add_f32_e32 v0, v6, v0
	ds_bpermute_b32 v3, v62, v2
	v_pk_mul_f32 v[8:9], v[74:75], v[74:75]
	v_add_f32_e32 v0, v7, v0
	v_add_f32_e32 v0, v8, v0
	v_pk_mul_f32 v[10:11], v[42:43], v[42:43]
	v_add_f32_e32 v0, v9, v0
	v_add_f32_e32 v0, v10, v0
	v_pk_mul_f32 v[12:13], v[44:45], v[44:45]
	v_add_f32_e32 v0, v11, v0
	s_waitcnt lgkmcnt(0)
	v_add_f32_e32 v2, v2, v3
	v_add_f32_e32 v0, v12, v0
	ds_bpermute_b32 v3, v63, v2
	v_pk_mul_f32 v[14:15], v[46:47], v[46:47]
	v_add_f32_e32 v0, v13, v0
	v_add_f32_e32 v0, v14, v0
	v_pk_mul_f32 v[16:17], v[48:49], v[48:49]
	v_add_f32_e32 v0, v15, v0
	v_add_f32_e32 v0, v16, v0
	v_add_f32_e32 v0, v17, v0
	s_waitcnt lgkmcnt(0)
	v_add_f32_e32 v2, v2, v3
	ds_bpermute_b32 v4, v61, v0
	ds_bpermute_b32 v3, v64, v2
	s_waitcnt lgkmcnt(1)
	v_add_f32_e32 v0, v0, v4
	s_waitcnt lgkmcnt(0)
	v_add_f32_e32 v11, v2, v3
	ds_bpermute_b32 v10, v62, v0
	ds_bpermute_b32 v12, v65, v11
	s_nop 1
	v_mov_b32_e32 v2, v140
	v_mov_b32_e32 v3, v141
	v_mov_b32_e32 v4, v142
	v_mov_b32_e32 v5, v143
	s_nop 1
	v_mov_b32_e32 v6, v144
	v_mov_b32_e32 v7, v145
	v_mov_b32_e32 v8, v146
	v_mov_b32_e32 v9, v147
	s_waitcnt lgkmcnt(1)
	v_add_f32_e32 v0, v0, v10
	s_waitcnt lgkmcnt(0)
	v_add_f32_e32 v59, v11, v12
	s_nop 1
	v_mov_b32_e32 v10, v148
	v_mov_b32_e32 v11, v149
	v_mov_b32_e32 v12, v150
	v_mov_b32_e32 v13, v151
	s_nop 1
	v_mov_b32_e32 v14, v152
	v_mov_b32_e32 v15, v153
	v_mov_b32_e32 v16, v154
	v_mov_b32_e32 v17, v155
	ds_bpermute_b32 v66, v60, v59
	ds_bpermute_b32 v58, v63, v0
	s_waitcnt lgkmcnt(1)
	v_add_f32_e32 v59, v59, v66
	v_fmamk_f32 v59, v59, 0x3a800000, v202
	s_waitcnt lgkmcnt(0)
	v_add_f32_e32 v0, v0, v58
	v_mul_f32_e32 v66, 0x4f800000, v59
	v_cmp_gt_f32_e32 vcc, s3, v59
	ds_bpermute_b32 v58, v64, v0
	s_waitcnt lgkmcnt(0)
	v_add_f32_e32 v0, v0, v58
	v_cndmask_b32_e32 v59, v59, v66, vcc
	v_sqrt_f32_e32 v66, v59
	s_nop 0
	v_add_u32_e32 v58, -1, v66
	v_add_u32_e32 v67, 1, v66
	v_fma_f32 v76, -v58, v66, v59
	v_fma_f32 v77, -v67, v66, v59
	v_cmp_ge_f32_e64 s[16:17], 0, v76
	s_nop 1
	v_cndmask_b32_e64 v58, v66, v58, s[16:17]
	v_cmp_lt_f32_e64 s[16:17], 0, v77
	s_nop 1
	v_cndmask_b32_e64 v58, v58, v67, s[16:17]
	ds_bpermute_b32 v67, v65, v0
	v_mul_f32_e32 v66, 0x37800000, v58
	v_cndmask_b32_e32 v58, v58, v66, vcc
	v_cmp_class_f32_e32 vcc, v59, v205
	s_waitcnt lgkmcnt(0)
	v_add_f32_e32 v0, v0, v67
	ds_bpermute_b32 v67, v60, v0
	v_cndmask_b32_e32 v58, v58, v59, vcc
	v_div_scale_f32 v59, s[14:15], v58, v58, 1.0
	v_rcp_f32_e32 v66, v59
	s_waitcnt lgkmcnt(0)
	v_add_f32_e32 v0, v0, v67
	v_fmamk_f32 v0, v0, 0x3a800000, v202
	v_mul_f32_e32 v67, 0x4f800000, v0
	v_cmp_gt_f32_e64 s[16:17], s3, v0
	v_fma_f32 v76, -v59, v66, 1.0
	v_fmac_f32_e32 v66, v76, v66
	v_cndmask_b32_e64 v0, v0, v67, s[16:17]
	v_div_scale_f32 v76, vcc, 1.0, v58, 1.0
	v_sqrt_f32_e32 v67, v0
	v_mul_f32_e32 v77, v76, v66
	v_fma_f32 v78, -v59, v77, v76
	v_fmac_f32_e32 v77, v78, v66
	v_fma_f32 v59, -v59, v77, v76
	v_add_u32_e32 v76, -1, v67
	v_fma_f32 v78, -v76, v67, v0
	v_cmp_ge_f32_e64 s[18:19], 0, v78
	v_add_u32_e32 v78, 1, v67
	s_nop 0
	v_cndmask_b32_e64 v76, v67, v76, s[18:19]
	v_fma_f32 v67, -v78, v67, v0
	v_cmp_lt_f32_e64 s[18:19], 0, v67
	s_nop 1
	v_cndmask_b32_e64 v67, v76, v78, s[18:19]
	v_mul_f32_e32 v76, 0x37800000, v67
	v_cndmask_b32_e64 v67, v67, v76, s[16:17]
	v_cmp_class_f32_e64 s[16:17], v0, v205
	s_nop 1
	v_cndmask_b32_e64 v67, v67, v0, s[16:17]
	v_div_scale_f32 v76, s[2:3], v67, v67, 1.0
	v_rcp_f32_e32 v78, v76
	v_div_fmas_f32 v0, v59, v66, v77
	v_div_fixup_f32 v0, v0, v58, 1.0
	v_fma_f32 v58, -v76, v78, 1.0
	v_fmac_f32_e32 v78, v58, v78
	v_div_scale_f32 v58, vcc, 1.0, v67, 1.0
	v_mul_f32_e32 v59, v58, v78
	v_fma_f32 v66, -v76, v59, v58
	v_fmac_f32_e32 v59, v66, v78
	v_fma_f32 v58, -v76, v59, v58
	v_div_fmas_f32 v58, v58, v78, v59
	v_div_fixup_f32 v58, v58, v67, 1.0
	v_pk_mul_f32 v[66:67], v[68:69], v[58:59] op_sel_hi:[1,0]
	v_pk_mul_f32 v[68:69], v[70:71], v[58:59] op_sel_hi:[1,0]
	v_pk_mul_f32 v[70:71], v[72:73], v[58:59] op_sel_hi:[1,0]
	v_pk_mul_f32 v[72:73], v[74:75], v[58:59] op_sel_hi:[1,0]
	s_nop 0
	v_pk_fma_f32 v[66:67], v[2:3], v[66:67], v[6:7]
	v_pk_fma_f32 v[68:69], v[4:5], v[68:69], v[8:9]
	s_nop 0
	v_pk_fma_f32 v[70:71], v[10:11], v[70:71], v[14:15]
	v_pk_fma_f32 v[72:73], v[12:13], v[72:73], v[16:17]
	v_cvt_pk_bf16_f32 v66, v66, v67
	v_cvt_pk_bf16_f32 v67, v68, v69
	v_cvt_pk_bf16_f32 v68, v70, v71
	v_cvt_pk_bf16_f32 v69, v72, v73
	global_store_dwordx4 v[30:31], v[66:69], off
	s_cbranch_scc1 .LBB0_2119
	v_pk_mul_f32 v[56:57], v[56:57], v[0:1] op_sel_hi:[1,0]
	s_nop 0
	v_pk_fma_f32 v[2:3], v[2:3], v[56:57], v[6:7]
	v_pk_mul_f32 v[6:7], v[54:55], v[0:1] op_sel_hi:[1,0]
	v_cvt_pk_bf16_f32 v2, v2, v3
	v_pk_fma_f32 v[4:5], v[4:5], v[6:7], v[8:9]
	v_pk_mul_f32 v[6:7], v[52:53], v[0:1] op_sel_hi:[1,0]
	v_pk_mul_f32 v[8:9], v[50:51], v[0:1] op_sel_hi:[1,0]
	v_pk_fma_f32 v[6:7], v[10:11], v[6:7], v[14:15]
	v_pk_fma_f32 v[8:9], v[12:13], v[8:9], v[16:17]
	v_cvt_pk_bf16_f32 v3, v4, v5
	v_cvt_pk_bf16_f32 v4, v6, v7
	v_cvt_pk_bf16_f32 v5, v8, v9
	global_store_dwordx4 v[28:29], v[2:5], off
.LBB0_2119:
	s_nop 1
	v_mov_b32_e32 v2, v156
	v_mov_b32_e32 v3, v157
	v_mov_b32_e32 v4, v158
	v_mov_b32_e32 v5, v159
	s_nop 0
	s_nop 1
	v_mov_b32_e32 v10, v160
	v_mov_b32_e32 v11, v161
	v_mov_b32_e32 v12, v162
	v_mov_b32_e32 v13, v163
	s_nop 1
	v_mov_b32_e32 v6, v164
	v_mov_b32_e32 v7, v165
	v_mov_b32_e32 v8, v166
	v_mov_b32_e32 v9, v167
	s_nop 1
	v_mov_b32_e32 v14, v168
	v_mov_b32_e32 v15, v169
	v_mov_b32_e32 v16, v170
	v_mov_b32_e32 v17, v171
	v_mov_b32_e32 v59, v58
	v_pk_mul_f32 v[42:43], v[42:43], v[58:59]
	v_pk_mul_f32 v[44:45], v[44:45], v[58:59]
	v_pk_mul_f32 v[46:47], v[46:47], v[58:59]
	v_pk_mul_f32 v[48:49], v[48:49], v[58:59]
	s_andn2_b64 vcc, exec, s[20:21]
	s_nop 0
	v_pk_fma_f32 v[46:47], v[46:47], v[2:3], v[6:7]
	s_nop 0
	v_pk_fma_f32 v[42:43], v[42:43], v[10:11], v[14:15]
	v_pk_fma_f32 v[44:45], v[44:45], v[12:13], v[16:17]
	v_pk_fma_f32 v[48:49], v[48:49], v[4:5], v[8:9]
	v_cvt_pk_bf16_f32 v42, v42, v43
	v_cvt_pk_bf16_f32 v43, v44, v45
	v_cvt_pk_bf16_f32 v44, v46, v47
	v_cvt_pk_bf16_f32 v45, v48, v49
	global_store_dwordx4 v[30:31], v[42:45], off offset:1024
	s_cbranch_vccnz .LBB0_2116
	v_pk_mul_f32 v[30:31], v[40:41], v[0:1] op_sel_hi:[1,0]
	s_nop 0
	v_pk_fma_f32 v[10:11], v[30:31], v[10:11], v[14:15]
	v_pk_mul_f32 v[14:15], v[36:37], v[0:1] op_sel_hi:[1,0]
	s_nop 0
	v_pk_fma_f32 v[12:13], v[14:15], v[12:13], v[16:17]
	v_pk_mul_f32 v[14:15], v[34:35], v[0:1] op_sel_hi:[1,0]
	s_nop 0
	v_pk_fma_f32 v[6:7], v[14:15], v[2:3], v[6:7]
	v_pk_mul_f32 v[2:3], v[32:33], v[0:1] op_sel_hi:[1,0]
	s_nop 0
	v_pk_fma_f32 v[8:9], v[2:3], v[4:5], v[8:9]
	v_cvt_pk_bf16_f32 v2, v10, v11
	v_cvt_pk_bf16_f32 v3, v12, v13
	v_cvt_pk_bf16_f32 v4, v6, v7
	v_cvt_pk_bf16_f32 v5, v8, v9
	global_store_dwordx4 v[28:29], v[2:5], off offset:1024
	s_branch .LBB0_2116
